# P0 cached log-forget prefix sums: hand-written DPP wave scan (row_shr/row_bcast) replaces the 390-hop ds_bpermute scan run by one wave per workgroup
# speedup vs baseline: 1.0161x; 1.0040x over previous
.LBB0_66:
	s_or_b64 exec, exec, s[8:9]
	s_cmpk_lt_i32 s96, 0x100
	s_cselect_b64 s[0:1], -1, 0
	s_and_b64 s[0:1], s[6:7], s[0:1]
	s_ashr_i32 s97, s96, 31
	s_ashr_i32 s73, s72, 31
	s_and_saveexec_b64 s[24:25], s[0:1]
	s_cbranch_execz .LBB0_197
	v_mbcnt_lo_u32_b32 v2, -1, 0
	v_mbcnt_hi_u32_b32 v2, -1, v2
	v_lshlrev_b32_e32 v6, 5, v2
	v_mov_b32_e32 v7, 0
	v_lshlrev_b32_e32 v8, 2, v2
	v_mov_b32_e32 v9, 0
	v_lshlrev_b32_e32 v11, 14, v137
	v_add_u32_e32 v10, v11, v8
	s_mov_b64 s[42:43], 0x1000
	s_mov_b32 s69, s96
.LBB0_69:
	v_readlane_b32 s20, v245, 37
	v_readlane_b32 s21, v245, 38
	s_ashr_i32 s40, s69, 3
	s_load_dwordx2 s[30:31], s[20:21], 0x20
	s_ashr_i32 s41, s40, 31
	s_lshl_b64 s[40:41], s[40:41], 17
	s_and_b32 s38, s69, 7
	s_lshl_b32 s38, s38, 2
	s_mul_i32 s44, s69, 0x4100
	s_mul_hi_i32 s45, s69, 0x4100
	s_add_u32 s44, s34, s44
	s_addc_u32 s45, s35, s45
	s_add_u32 s44, s44, 0x1c00000
	s_addc_u32 s45, s45, 0
	s_waitcnt lgkmcnt(0)
	s_add_u32 s30, s30, s40
	s_addc_u32 s31, s31, s41
	s_add_u32 s30, s30, s38
	s_addc_u32 s31, s31, 0
	v_lshl_add_u64 v[4:5], s[30:31], 0, v[6:7]
	v_lshl_add_u64 v[12:13], s[44:45], 0, v[8:9]
	global_load_dword v64, v[4:5], off
	global_load_dword v65, v[4:5], off offset:2048
	v_lshl_add_u64 v[4:5], v[4:5], 0, s[42:43]
	global_load_dword v66, v[4:5], off
	global_load_dword v67, v[4:5], off offset:2048
	v_lshl_add_u64 v[4:5], v[4:5], 0, s[42:43]
	global_load_dword v68, v[4:5], off
	global_load_dword v69, v[4:5], off offset:2048
	v_lshl_add_u64 v[4:5], v[4:5], 0, s[42:43]
	global_load_dword v70, v[4:5], off
	global_load_dword v71, v[4:5], off offset:2048
	v_lshl_add_u64 v[4:5], v[4:5], 0, s[42:43]
	global_load_dword v72, v[4:5], off
	global_load_dword v73, v[4:5], off offset:2048
	v_lshl_add_u64 v[4:5], v[4:5], 0, s[42:43]
	global_load_dword v74, v[4:5], off
	global_load_dword v75, v[4:5], off offset:2048
	v_lshl_add_u64 v[4:5], v[4:5], 0, s[42:43]
	global_load_dword v76, v[4:5], off
	global_load_dword v77, v[4:5], off offset:2048
	v_lshl_add_u64 v[4:5], v[4:5], 0, s[42:43]
	global_load_dword v78, v[4:5], off
	global_load_dword v79, v[4:5], off offset:2048
	v_lshl_add_u64 v[4:5], v[4:5], 0, s[42:43]
	global_load_dword v80, v[4:5], off
	global_load_dword v81, v[4:5], off offset:2048
	v_lshl_add_u64 v[4:5], v[4:5], 0, s[42:43]
	global_load_dword v82, v[4:5], off
	global_load_dword v83, v[4:5], off offset:2048
	v_lshl_add_u64 v[4:5], v[4:5], 0, s[42:43]
	global_load_dword v84, v[4:5], off
	global_load_dword v85, v[4:5], off offset:2048
	v_lshl_add_u64 v[4:5], v[4:5], 0, s[42:43]
	global_load_dword v86, v[4:5], off
	global_load_dword v87, v[4:5], off offset:2048
	v_lshl_add_u64 v[4:5], v[4:5], 0, s[42:43]
	global_load_dword v88, v[4:5], off
	global_load_dword v89, v[4:5], off offset:2048
	v_lshl_add_u64 v[4:5], v[4:5], 0, s[42:43]
	global_load_dword v90, v[4:5], off
	global_load_dword v91, v[4:5], off offset:2048
	v_lshl_add_u64 v[4:5], v[4:5], 0, s[42:43]
	global_load_dword v92, v[4:5], off
	global_load_dword v93, v[4:5], off offset:2048
	v_lshl_add_u64 v[4:5], v[4:5], 0, s[42:43]
	global_load_dword v94, v[4:5], off
	global_load_dword v95, v[4:5], off offset:2048
	v_lshl_add_u64 v[4:5], v[4:5], 0, s[42:43]
	global_load_dword v96, v[4:5], off
	global_load_dword v97, v[4:5], off offset:2048
	v_lshl_add_u64 v[4:5], v[4:5], 0, s[42:43]
	global_load_dword v98, v[4:5], off
	global_load_dword v99, v[4:5], off offset:2048
	v_lshl_add_u64 v[4:5], v[4:5], 0, s[42:43]
	global_load_dword v100, v[4:5], off
	global_load_dword v101, v[4:5], off offset:2048
	v_lshl_add_u64 v[4:5], v[4:5], 0, s[42:43]
	global_load_dword v102, v[4:5], off
	global_load_dword v103, v[4:5], off offset:2048
	v_lshl_add_u64 v[4:5], v[4:5], 0, s[42:43]
	global_load_dword v104, v[4:5], off
	global_load_dword v105, v[4:5], off offset:2048
	v_lshl_add_u64 v[4:5], v[4:5], 0, s[42:43]
	global_load_dword v106, v[4:5], off
	global_load_dword v107, v[4:5], off offset:2048
	v_lshl_add_u64 v[4:5], v[4:5], 0, s[42:43]
	global_load_dword v108, v[4:5], off
	global_load_dword v109, v[4:5], off offset:2048
	v_lshl_add_u64 v[4:5], v[4:5], 0, s[42:43]
	global_load_dword v110, v[4:5], off
	global_load_dword v111, v[4:5], off offset:2048
	v_lshl_add_u64 v[4:5], v[4:5], 0, s[42:43]
	global_load_dword v112, v[4:5], off
	global_load_dword v113, v[4:5], off offset:2048
	v_lshl_add_u64 v[4:5], v[4:5], 0, s[42:43]
	global_load_dword v114, v[4:5], off
	global_load_dword v115, v[4:5], off offset:2048
	v_lshl_add_u64 v[4:5], v[4:5], 0, s[42:43]
	global_load_dword v116, v[4:5], off
	global_load_dword v117, v[4:5], off offset:2048
	v_lshl_add_u64 v[4:5], v[4:5], 0, s[42:43]
	global_load_dword v118, v[4:5], off
	global_load_dword v119, v[4:5], off offset:2048
	v_lshl_add_u64 v[4:5], v[4:5], 0, s[42:43]
	global_load_dword v120, v[4:5], off
	global_load_dword v121, v[4:5], off offset:2048
	v_lshl_add_u64 v[4:5], v[4:5], 0, s[42:43]
	global_load_dword v122, v[4:5], off
	global_load_dword v123, v[4:5], off offset:2048
	v_lshl_add_u64 v[4:5], v[4:5], 0, s[42:43]
	global_load_dword v124, v[4:5], off
	global_load_dword v125, v[4:5], off offset:2048
	v_lshl_add_u64 v[4:5], v[4:5], 0, s[42:43]
	global_load_dword v126, v[4:5], off
	global_load_dword v127, v[4:5], off offset:2048
	s_waitcnt vmcnt(56)
	v_add_f32_dpp v64, v64, v64 row_shr:1 row_mask:0xf bank_mask:0xf
	v_add_f32_dpp v65, v65, v65 row_shr:1 row_mask:0xf bank_mask:0xf
	v_add_f32_dpp v66, v66, v66 row_shr:1 row_mask:0xf bank_mask:0xf
	v_add_f32_dpp v67, v67, v67 row_shr:1 row_mask:0xf bank_mask:0xf
	v_add_f32_dpp v68, v68, v68 row_shr:1 row_mask:0xf bank_mask:0xf
	v_add_f32_dpp v69, v69, v69 row_shr:1 row_mask:0xf bank_mask:0xf
	v_add_f32_dpp v70, v70, v70 row_shr:1 row_mask:0xf bank_mask:0xf
	v_add_f32_dpp v71, v71, v71 row_shr:1 row_mask:0xf bank_mask:0xf
	v_add_f32_dpp v64, v64, v64 row_shr:2 row_mask:0xf bank_mask:0xf
	v_add_f32_dpp v65, v65, v65 row_shr:2 row_mask:0xf bank_mask:0xf
	v_add_f32_dpp v66, v66, v66 row_shr:2 row_mask:0xf bank_mask:0xf
	v_add_f32_dpp v67, v67, v67 row_shr:2 row_mask:0xf bank_mask:0xf
	v_add_f32_dpp v68, v68, v68 row_shr:2 row_mask:0xf bank_mask:0xf
	v_add_f32_dpp v69, v69, v69 row_shr:2 row_mask:0xf bank_mask:0xf
	v_add_f32_dpp v70, v70, v70 row_shr:2 row_mask:0xf bank_mask:0xf
	v_add_f32_dpp v71, v71, v71 row_shr:2 row_mask:0xf bank_mask:0xf
	v_add_f32_dpp v64, v64, v64 row_shr:4 row_mask:0xf bank_mask:0xf
	v_add_f32_dpp v65, v65, v65 row_shr:4 row_mask:0xf bank_mask:0xf
	v_add_f32_dpp v66, v66, v66 row_shr:4 row_mask:0xf bank_mask:0xf
	v_add_f32_dpp v67, v67, v67 row_shr:4 row_mask:0xf bank_mask:0xf
	v_add_f32_dpp v68, v68, v68 row_shr:4 row_mask:0xf bank_mask:0xf
	v_add_f32_dpp v69, v69, v69 row_shr:4 row_mask:0xf bank_mask:0xf
	v_add_f32_dpp v70, v70, v70 row_shr:4 row_mask:0xf bank_mask:0xf
	v_add_f32_dpp v71, v71, v71 row_shr:4 row_mask:0xf bank_mask:0xf
	v_add_f32_dpp v64, v64, v64 row_shr:8 row_mask:0xf bank_mask:0xf
	v_add_f32_dpp v65, v65, v65 row_shr:8 row_mask:0xf bank_mask:0xf
	v_add_f32_dpp v66, v66, v66 row_shr:8 row_mask:0xf bank_mask:0xf
	v_add_f32_dpp v67, v67, v67 row_shr:8 row_mask:0xf bank_mask:0xf
	v_add_f32_dpp v68, v68, v68 row_shr:8 row_mask:0xf bank_mask:0xf
	v_add_f32_dpp v69, v69, v69 row_shr:8 row_mask:0xf bank_mask:0xf
	v_add_f32_dpp v70, v70, v70 row_shr:8 row_mask:0xf bank_mask:0xf
	v_add_f32_dpp v71, v71, v71 row_shr:8 row_mask:0xf bank_mask:0xf
	v_add_f32_dpp v64, v64, v64 row_bcast:15 row_mask:0xa bank_mask:0xf
	v_add_f32_dpp v65, v65, v65 row_bcast:15 row_mask:0xa bank_mask:0xf
	v_add_f32_dpp v66, v66, v66 row_bcast:15 row_mask:0xa bank_mask:0xf
	v_add_f32_dpp v67, v67, v67 row_bcast:15 row_mask:0xa bank_mask:0xf
	v_add_f32_dpp v68, v68, v68 row_bcast:15 row_mask:0xa bank_mask:0xf
	v_add_f32_dpp v69, v69, v69 row_bcast:15 row_mask:0xa bank_mask:0xf
	v_add_f32_dpp v70, v70, v70 row_bcast:15 row_mask:0xa bank_mask:0xf
	v_add_f32_dpp v71, v71, v71 row_bcast:15 row_mask:0xa bank_mask:0xf
	v_add_f32_dpp v64, v64, v64 row_bcast:31 row_mask:0xc bank_mask:0xf
	v_add_f32_dpp v65, v65, v65 row_bcast:31 row_mask:0xc bank_mask:0xf
	v_add_f32_dpp v66, v66, v66 row_bcast:31 row_mask:0xc bank_mask:0xf
	v_add_f32_dpp v67, v67, v67 row_bcast:31 row_mask:0xc bank_mask:0xf
	v_add_f32_dpp v68, v68, v68 row_bcast:31 row_mask:0xc bank_mask:0xf
	v_add_f32_dpp v69, v69, v69 row_bcast:31 row_mask:0xc bank_mask:0xf
	v_add_f32_dpp v70, v70, v70 row_bcast:31 row_mask:0xc bank_mask:0xf
	v_add_f32_dpp v71, v71, v71 row_bcast:31 row_mask:0xc bank_mask:0xf
	s_waitcnt vmcnt(48)
	v_add_f32_dpp v72, v72, v72 row_shr:1 row_mask:0xf bank_mask:0xf
	v_add_f32_dpp v73, v73, v73 row_shr:1 row_mask:0xf bank_mask:0xf
	v_add_f32_dpp v74, v74, v74 row_shr:1 row_mask:0xf bank_mask:0xf
	v_add_f32_dpp v75, v75, v75 row_shr:1 row_mask:0xf bank_mask:0xf
	v_add_f32_dpp v76, v76, v76 row_shr:1 row_mask:0xf bank_mask:0xf
	v_add_f32_dpp v77, v77, v77 row_shr:1 row_mask:0xf bank_mask:0xf
	v_add_f32_dpp v78, v78, v78 row_shr:1 row_mask:0xf bank_mask:0xf
	v_add_f32_dpp v79, v79, v79 row_shr:1 row_mask:0xf bank_mask:0xf
	v_add_f32_dpp v72, v72, v72 row_shr:2 row_mask:0xf bank_mask:0xf
	v_add_f32_dpp v73, v73, v73 row_shr:2 row_mask:0xf bank_mask:0xf
	v_add_f32_dpp v74, v74, v74 row_shr:2 row_mask:0xf bank_mask:0xf
	v_add_f32_dpp v75, v75, v75 row_shr:2 row_mask:0xf bank_mask:0xf
	v_add_f32_dpp v76, v76, v76 row_shr:2 row_mask:0xf bank_mask:0xf
	v_add_f32_dpp v77, v77, v77 row_shr:2 row_mask:0xf bank_mask:0xf
	v_add_f32_dpp v78, v78, v78 row_shr:2 row_mask:0xf bank_mask:0xf
	v_add_f32_dpp v79, v79, v79 row_shr:2 row_mask:0xf bank_mask:0xf
	v_add_f32_dpp v72, v72, v72 row_shr:4 row_mask:0xf bank_mask:0xf
	v_add_f32_dpp v73, v73, v73 row_shr:4 row_mask:0xf bank_mask:0xf
	v_add_f32_dpp v74, v74, v74 row_shr:4 row_mask:0xf bank_mask:0xf
	v_add_f32_dpp v75, v75, v75 row_shr:4 row_mask:0xf bank_mask:0xf
	v_add_f32_dpp v76, v76, v76 row_shr:4 row_mask:0xf bank_mask:0xf
	v_add_f32_dpp v77, v77, v77 row_shr:4 row_mask:0xf bank_mask:0xf
	v_add_f32_dpp v78, v78, v78 row_shr:4 row_mask:0xf bank_mask:0xf
	v_add_f32_dpp v79, v79, v79 row_shr:4 row_mask:0xf bank_mask:0xf
	v_add_f32_dpp v72, v72, v72 row_shr:8 row_mask:0xf bank_mask:0xf
	v_add_f32_dpp v73, v73, v73 row_shr:8 row_mask:0xf bank_mask:0xf
	v_add_f32_dpp v74, v74, v74 row_shr:8 row_mask:0xf bank_mask:0xf
	v_add_f32_dpp v75, v75, v75 row_shr:8 row_mask:0xf bank_mask:0xf
	v_add_f32_dpp v76, v76, v76 row_shr:8 row_mask:0xf bank_mask:0xf
	v_add_f32_dpp v77, v77, v77 row_shr:8 row_mask:0xf bank_mask:0xf
	v_add_f32_dpp v78, v78, v78 row_shr:8 row_mask:0xf bank_mask:0xf
	v_add_f32_dpp v79, v79, v79 row_shr:8 row_mask:0xf bank_mask:0xf
	v_add_f32_dpp v72, v72, v72 row_bcast:15 row_mask:0xa bank_mask:0xf
	v_add_f32_dpp v73, v73, v73 row_bcast:15 row_mask:0xa bank_mask:0xf
	v_add_f32_dpp v74, v74, v74 row_bcast:15 row_mask:0xa bank_mask:0xf
	v_add_f32_dpp v75, v75, v75 row_bcast:15 row_mask:0xa bank_mask:0xf
	v_add_f32_dpp v76, v76, v76 row_bcast:15 row_mask:0xa bank_mask:0xf
	v_add_f32_dpp v77, v77, v77 row_bcast:15 row_mask:0xa bank_mask:0xf
	v_add_f32_dpp v78, v78, v78 row_bcast:15 row_mask:0xa bank_mask:0xf
	v_add_f32_dpp v79, v79, v79 row_bcast:15 row_mask:0xa bank_mask:0xf
	v_add_f32_dpp v72, v72, v72 row_bcast:31 row_mask:0xc bank_mask:0xf
	v_add_f32_dpp v73, v73, v73 row_bcast:31 row_mask:0xc bank_mask:0xf
	v_add_f32_dpp v74, v74, v74 row_bcast:31 row_mask:0xc bank_mask:0xf
	v_add_f32_dpp v75, v75, v75 row_bcast:31 row_mask:0xc bank_mask:0xf
	v_add_f32_dpp v76, v76, v76 row_bcast:31 row_mask:0xc bank_mask:0xf
	v_add_f32_dpp v77, v77, v77 row_bcast:31 row_mask:0xc bank_mask:0xf
	v_add_f32_dpp v78, v78, v78 row_bcast:31 row_mask:0xc bank_mask:0xf
	v_add_f32_dpp v79, v79, v79 row_bcast:31 row_mask:0xc bank_mask:0xf
	s_waitcnt vmcnt(40)
	v_add_f32_dpp v80, v80, v80 row_shr:1 row_mask:0xf bank_mask:0xf
	v_add_f32_dpp v81, v81, v81 row_shr:1 row_mask:0xf bank_mask:0xf
	v_add_f32_dpp v82, v82, v82 row_shr:1 row_mask:0xf bank_mask:0xf
	v_add_f32_dpp v83, v83, v83 row_shr:1 row_mask:0xf bank_mask:0xf
	v_add_f32_dpp v84, v84, v84 row_shr:1 row_mask:0xf bank_mask:0xf
	v_add_f32_dpp v85, v85, v85 row_shr:1 row_mask:0xf bank_mask:0xf
	v_add_f32_dpp v86, v86, v86 row_shr:1 row_mask:0xf bank_mask:0xf
	v_add_f32_dpp v87, v87, v87 row_shr:1 row_mask:0xf bank_mask:0xf
	v_add_f32_dpp v80, v80, v80 row_shr:2 row_mask:0xf bank_mask:0xf
	v_add_f32_dpp v81, v81, v81 row_shr:2 row_mask:0xf bank_mask:0xf
	v_add_f32_dpp v82, v82, v82 row_shr:2 row_mask:0xf bank_mask:0xf
	v_add_f32_dpp v83, v83, v83 row_shr:2 row_mask:0xf bank_mask:0xf
	v_add_f32_dpp v84, v84, v84 row_shr:2 row_mask:0xf bank_mask:0xf
	v_add_f32_dpp v85, v85, v85 row_shr:2 row_mask:0xf bank_mask:0xf
	v_add_f32_dpp v86, v86, v86 row_shr:2 row_mask:0xf bank_mask:0xf
	v_add_f32_dpp v87, v87, v87 row_shr:2 row_mask:0xf bank_mask:0xf
	v_add_f32_dpp v80, v80, v80 row_shr:4 row_mask:0xf bank_mask:0xf
	v_add_f32_dpp v81, v81, v81 row_shr:4 row_mask:0xf bank_mask:0xf
	v_add_f32_dpp v82, v82, v82 row_shr:4 row_mask:0xf bank_mask:0xf
	v_add_f32_dpp v83, v83, v83 row_shr:4 row_mask:0xf bank_mask:0xf
	v_add_f32_dpp v84, v84, v84 row_shr:4 row_mask:0xf bank_mask:0xf
	v_add_f32_dpp v85, v85, v85 row_shr:4 row_mask:0xf bank_mask:0xf
	v_add_f32_dpp v86, v86, v86 row_shr:4 row_mask:0xf bank_mask:0xf
	v_add_f32_dpp v87, v87, v87 row_shr:4 row_mask:0xf bank_mask:0xf
	v_add_f32_dpp v80, v80, v80 row_shr:8 row_mask:0xf bank_mask:0xf
	v_add_f32_dpp v81, v81, v81 row_shr:8 row_mask:0xf bank_mask:0xf
	v_add_f32_dpp v82, v82, v82 row_shr:8 row_mask:0xf bank_mask:0xf
	v_add_f32_dpp v83, v83, v83 row_shr:8 row_mask:0xf bank_mask:0xf
	v_add_f32_dpp v84, v84, v84 row_shr:8 row_mask:0xf bank_mask:0xf
	v_add_f32_dpp v85, v85, v85 row_shr:8 row_mask:0xf bank_mask:0xf
	v_add_f32_dpp v86, v86, v86 row_shr:8 row_mask:0xf bank_mask:0xf
	v_add_f32_dpp v87, v87, v87 row_shr:8 row_mask:0xf bank_mask:0xf
	v_add_f32_dpp v80, v80, v80 row_bcast:15 row_mask:0xa bank_mask:0xf
	v_add_f32_dpp v81, v81, v81 row_bcast:15 row_mask:0xa bank_mask:0xf
	v_add_f32_dpp v82, v82, v82 row_bcast:15 row_mask:0xa bank_mask:0xf
	v_add_f32_dpp v83, v83, v83 row_bcast:15 row_mask:0xa bank_mask:0xf
	v_add_f32_dpp v84, v84, v84 row_bcast:15 row_mask:0xa bank_mask:0xf
	v_add_f32_dpp v85, v85, v85 row_bcast:15 row_mask:0xa bank_mask:0xf
	v_add_f32_dpp v86, v86, v86 row_bcast:15 row_mask:0xa bank_mask:0xf
	v_add_f32_dpp v87, v87, v87 row_bcast:15 row_mask:0xa bank_mask:0xf
	v_add_f32_dpp v80, v80, v80 row_bcast:31 row_mask:0xc bank_mask:0xf
	v_add_f32_dpp v81, v81, v81 row_bcast:31 row_mask:0xc bank_mask:0xf
	v_add_f32_dpp v82, v82, v82 row_bcast:31 row_mask:0xc bank_mask:0xf
	v_add_f32_dpp v83, v83, v83 row_bcast:31 row_mask:0xc bank_mask:0xf
	v_add_f32_dpp v84, v84, v84 row_bcast:31 row_mask:0xc bank_mask:0xf
	v_add_f32_dpp v85, v85, v85 row_bcast:31 row_mask:0xc bank_mask:0xf
	v_add_f32_dpp v86, v86, v86 row_bcast:31 row_mask:0xc bank_mask:0xf
	v_add_f32_dpp v87, v87, v87 row_bcast:31 row_mask:0xc bank_mask:0xf
	s_waitcnt vmcnt(32)
	v_add_f32_dpp v88, v88, v88 row_shr:1 row_mask:0xf bank_mask:0xf
	v_add_f32_dpp v89, v89, v89 row_shr:1 row_mask:0xf bank_mask:0xf
	v_add_f32_dpp v90, v90, v90 row_shr:1 row_mask:0xf bank_mask:0xf
	v_add_f32_dpp v91, v91, v91 row_shr:1 row_mask:0xf bank_mask:0xf
	v_add_f32_dpp v92, v92, v92 row_shr:1 row_mask:0xf bank_mask:0xf
	v_add_f32_dpp v93, v93, v93 row_shr:1 row_mask:0xf bank_mask:0xf
	v_add_f32_dpp v94, v94, v94 row_shr:1 row_mask:0xf bank_mask:0xf
	v_add_f32_dpp v95, v95, v95 row_shr:1 row_mask:0xf bank_mask:0xf
	v_add_f32_dpp v88, v88, v88 row_shr:2 row_mask:0xf bank_mask:0xf
	v_add_f32_dpp v89, v89, v89 row_shr:2 row_mask:0xf bank_mask:0xf
	v_add_f32_dpp v90, v90, v90 row_shr:2 row_mask:0xf bank_mask:0xf
	v_add_f32_dpp v91, v91, v91 row_shr:2 row_mask:0xf bank_mask:0xf
	v_add_f32_dpp v92, v92, v92 row_shr:2 row_mask:0xf bank_mask:0xf
	v_add_f32_dpp v93, v93, v93 row_shr:2 row_mask:0xf bank_mask:0xf
	v_add_f32_dpp v94, v94, v94 row_shr:2 row_mask:0xf bank_mask:0xf
	v_add_f32_dpp v95, v95, v95 row_shr:2 row_mask:0xf bank_mask:0xf
	v_add_f32_dpp v88, v88, v88 row_shr:4 row_mask:0xf bank_mask:0xf
	v_add_f32_dpp v89, v89, v89 row_shr:4 row_mask:0xf bank_mask:0xf
	v_add_f32_dpp v90, v90, v90 row_shr:4 row_mask:0xf bank_mask:0xf
	v_add_f32_dpp v91, v91, v91 row_shr:4 row_mask:0xf bank_mask:0xf
	v_add_f32_dpp v92, v92, v92 row_shr:4 row_mask:0xf bank_mask:0xf
	v_add_f32_dpp v93, v93, v93 row_shr:4 row_mask:0xf bank_mask:0xf
	v_add_f32_dpp v94, v94, v94 row_shr:4 row_mask:0xf bank_mask:0xf
	v_add_f32_dpp v95, v95, v95 row_shr:4 row_mask:0xf bank_mask:0xf
	v_add_f32_dpp v88, v88, v88 row_shr:8 row_mask:0xf bank_mask:0xf
	v_add_f32_dpp v89, v89, v89 row_shr:8 row_mask:0xf bank_mask:0xf
	v_add_f32_dpp v90, v90, v90 row_shr:8 row_mask:0xf bank_mask:0xf
	v_add_f32_dpp v91, v91, v91 row_shr:8 row_mask:0xf bank_mask:0xf
	v_add_f32_dpp v92, v92, v92 row_shr:8 row_mask:0xf bank_mask:0xf
	v_add_f32_dpp v93, v93, v93 row_shr:8 row_mask:0xf bank_mask:0xf
	v_add_f32_dpp v94, v94, v94 row_shr:8 row_mask:0xf bank_mask:0xf
	v_add_f32_dpp v95, v95, v95 row_shr:8 row_mask:0xf bank_mask:0xf
	v_add_f32_dpp v88, v88, v88 row_bcast:15 row_mask:0xa bank_mask:0xf
	v_add_f32_dpp v89, v89, v89 row_bcast:15 row_mask:0xa bank_mask:0xf
	v_add_f32_dpp v90, v90, v90 row_bcast:15 row_mask:0xa bank_mask:0xf
	v_add_f32_dpp v91, v91, v91 row_bcast:15 row_mask:0xa bank_mask:0xf
	v_add_f32_dpp v92, v92, v92 row_bcast:15 row_mask:0xa bank_mask:0xf
	v_add_f32_dpp v93, v93, v93 row_bcast:15 row_mask:0xa bank_mask:0xf
	v_add_f32_dpp v94, v94, v94 row_bcast:15 row_mask:0xa bank_mask:0xf
	v_add_f32_dpp v95, v95, v95 row_bcast:15 row_mask:0xa bank_mask:0xf
	v_add_f32_dpp v88, v88, v88 row_bcast:31 row_mask:0xc bank_mask:0xf
	v_add_f32_dpp v89, v89, v89 row_bcast:31 row_mask:0xc bank_mask:0xf
	v_add_f32_dpp v90, v90, v90 row_bcast:31 row_mask:0xc bank_mask:0xf
	v_add_f32_dpp v91, v91, v91 row_bcast:31 row_mask:0xc bank_mask:0xf
	v_add_f32_dpp v92, v92, v92 row_bcast:31 row_mask:0xc bank_mask:0xf
	v_add_f32_dpp v93, v93, v93 row_bcast:31 row_mask:0xc bank_mask:0xf
	v_add_f32_dpp v94, v94, v94 row_bcast:31 row_mask:0xc bank_mask:0xf
	v_add_f32_dpp v95, v95, v95 row_bcast:31 row_mask:0xc bank_mask:0xf
	s_waitcnt vmcnt(24)
	v_add_f32_dpp v96, v96, v96 row_shr:1 row_mask:0xf bank_mask:0xf
	v_add_f32_dpp v97, v97, v97 row_shr:1 row_mask:0xf bank_mask:0xf
	v_add_f32_dpp v98, v98, v98 row_shr:1 row_mask:0xf bank_mask:0xf
	v_add_f32_dpp v99, v99, v99 row_shr:1 row_mask:0xf bank_mask:0xf
	v_add_f32_dpp v100, v100, v100 row_shr:1 row_mask:0xf bank_mask:0xf
	v_add_f32_dpp v101, v101, v101 row_shr:1 row_mask:0xf bank_mask:0xf
	v_add_f32_dpp v102, v102, v102 row_shr:1 row_mask:0xf bank_mask:0xf
	v_add_f32_dpp v103, v103, v103 row_shr:1 row_mask:0xf bank_mask:0xf
	v_add_f32_dpp v96, v96, v96 row_shr:2 row_mask:0xf bank_mask:0xf
	v_add_f32_dpp v97, v97, v97 row_shr:2 row_mask:0xf bank_mask:0xf
	v_add_f32_dpp v98, v98, v98 row_shr:2 row_mask:0xf bank_mask:0xf
	v_add_f32_dpp v99, v99, v99 row_shr:2 row_mask:0xf bank_mask:0xf
	v_add_f32_dpp v100, v100, v100 row_shr:2 row_mask:0xf bank_mask:0xf
	v_add_f32_dpp v101, v101, v101 row_shr:2 row_mask:0xf bank_mask:0xf
	v_add_f32_dpp v102, v102, v102 row_shr:2 row_mask:0xf bank_mask:0xf
	v_add_f32_dpp v103, v103, v103 row_shr:2 row_mask:0xf bank_mask:0xf
	v_add_f32_dpp v96, v96, v96 row_shr:4 row_mask:0xf bank_mask:0xf
	v_add_f32_dpp v97, v97, v97 row_shr:4 row_mask:0xf bank_mask:0xf
	v_add_f32_dpp v98, v98, v98 row_shr:4 row_mask:0xf bank_mask:0xf
	v_add_f32_dpp v99, v99, v99 row_shr:4 row_mask:0xf bank_mask:0xf
	v_add_f32_dpp v100, v100, v100 row_shr:4 row_mask:0xf bank_mask:0xf
	v_add_f32_dpp v101, v101, v101 row_shr:4 row_mask:0xf bank_mask:0xf
	v_add_f32_dpp v102, v102, v102 row_shr:4 row_mask:0xf bank_mask:0xf
	v_add_f32_dpp v103, v103, v103 row_shr:4 row_mask:0xf bank_mask:0xf
	v_add_f32_dpp v96, v96, v96 row_shr:8 row_mask:0xf bank_mask:0xf
	v_add_f32_dpp v97, v97, v97 row_shr:8 row_mask:0xf bank_mask:0xf
	v_add_f32_dpp v98, v98, v98 row_shr:8 row_mask:0xf bank_mask:0xf
	v_add_f32_dpp v99, v99, v99 row_shr:8 row_mask:0xf bank_mask:0xf
	v_add_f32_dpp v100, v100, v100 row_shr:8 row_mask:0xf bank_mask:0xf
	v_add_f32_dpp v101, v101, v101 row_shr:8 row_mask:0xf bank_mask:0xf
	v_add_f32_dpp v102, v102, v102 row_shr:8 row_mask:0xf bank_mask:0xf
	v_add_f32_dpp v103, v103, v103 row_shr:8 row_mask:0xf bank_mask:0xf
	v_add_f32_dpp v96, v96, v96 row_bcast:15 row_mask:0xa bank_mask:0xf
	v_add_f32_dpp v97, v97, v97 row_bcast:15 row_mask:0xa bank_mask:0xf
	v_add_f32_dpp v98, v98, v98 row_bcast:15 row_mask:0xa bank_mask:0xf
	v_add_f32_dpp v99, v99, v99 row_bcast:15 row_mask:0xa bank_mask:0xf
	v_add_f32_dpp v100, v100, v100 row_bcast:15 row_mask:0xa bank_mask:0xf
	v_add_f32_dpp v101, v101, v101 row_bcast:15 row_mask:0xa bank_mask:0xf
	v_add_f32_dpp v102, v102, v102 row_bcast:15 row_mask:0xa bank_mask:0xf
	v_add_f32_dpp v103, v103, v103 row_bcast:15 row_mask:0xa bank_mask:0xf
	v_add_f32_dpp v96, v96, v96 row_bcast:31 row_mask:0xc bank_mask:0xf
	v_add_f32_dpp v97, v97, v97 row_bcast:31 row_mask:0xc bank_mask:0xf
	v_add_f32_dpp v98, v98, v98 row_bcast:31 row_mask:0xc bank_mask:0xf
	v_add_f32_dpp v99, v99, v99 row_bcast:31 row_mask:0xc bank_mask:0xf
	v_add_f32_dpp v100, v100, v100 row_bcast:31 row_mask:0xc bank_mask:0xf
	v_add_f32_dpp v101, v101, v101 row_bcast:31 row_mask:0xc bank_mask:0xf
	v_add_f32_dpp v102, v102, v102 row_bcast:31 row_mask:0xc bank_mask:0xf
	v_add_f32_dpp v103, v103, v103 row_bcast:31 row_mask:0xc bank_mask:0xf
	s_waitcnt vmcnt(16)
	v_add_f32_dpp v104, v104, v104 row_shr:1 row_mask:0xf bank_mask:0xf
	v_add_f32_dpp v105, v105, v105 row_shr:1 row_mask:0xf bank_mask:0xf
	v_add_f32_dpp v106, v106, v106 row_shr:1 row_mask:0xf bank_mask:0xf
	v_add_f32_dpp v107, v107, v107 row_shr:1 row_mask:0xf bank_mask:0xf
	v_add_f32_dpp v108, v108, v108 row_shr:1 row_mask:0xf bank_mask:0xf
	v_add_f32_dpp v109, v109, v109 row_shr:1 row_mask:0xf bank_mask:0xf
	v_add_f32_dpp v110, v110, v110 row_shr:1 row_mask:0xf bank_mask:0xf
	v_add_f32_dpp v111, v111, v111 row_shr:1 row_mask:0xf bank_mask:0xf
	v_add_f32_dpp v104, v104, v104 row_shr:2 row_mask:0xf bank_mask:0xf
	v_add_f32_dpp v105, v105, v105 row_shr:2 row_mask:0xf bank_mask:0xf
	v_add_f32_dpp v106, v106, v106 row_shr:2 row_mask:0xf bank_mask:0xf
	v_add_f32_dpp v107, v107, v107 row_shr:2 row_mask:0xf bank_mask:0xf
	v_add_f32_dpp v108, v108, v108 row_shr:2 row_mask:0xf bank_mask:0xf
	v_add_f32_dpp v109, v109, v109 row_shr:2 row_mask:0xf bank_mask:0xf
	v_add_f32_dpp v110, v110, v110 row_shr:2 row_mask:0xf bank_mask:0xf
	v_add_f32_dpp v111, v111, v111 row_shr:2 row_mask:0xf bank_mask:0xf
	v_add_f32_dpp v104, v104, v104 row_shr:4 row_mask:0xf bank_mask:0xf
	v_add_f32_dpp v105, v105, v105 row_shr:4 row_mask:0xf bank_mask:0xf
	v_add_f32_dpp v106, v106, v106 row_shr:4 row_mask:0xf bank_mask:0xf
	v_add_f32_dpp v107, v107, v107 row_shr:4 row_mask:0xf bank_mask:0xf
	v_add_f32_dpp v108, v108, v108 row_shr:4 row_mask:0xf bank_mask:0xf
	v_add_f32_dpp v109, v109, v109 row_shr:4 row_mask:0xf bank_mask:0xf
	v_add_f32_dpp v110, v110, v110 row_shr:4 row_mask:0xf bank_mask:0xf
	v_add_f32_dpp v111, v111, v111 row_shr:4 row_mask:0xf bank_mask:0xf
	v_add_f32_dpp v104, v104, v104 row_shr:8 row_mask:0xf bank_mask:0xf
	v_add_f32_dpp v105, v105, v105 row_shr:8 row_mask:0xf bank_mask:0xf
	v_add_f32_dpp v106, v106, v106 row_shr:8 row_mask:0xf bank_mask:0xf
	v_add_f32_dpp v107, v107, v107 row_shr:8 row_mask:0xf bank_mask:0xf
	v_add_f32_dpp v108, v108, v108 row_shr:8 row_mask:0xf bank_mask:0xf
	v_add_f32_dpp v109, v109, v109 row_shr:8 row_mask:0xf bank_mask:0xf
	v_add_f32_dpp v110, v110, v110 row_shr:8 row_mask:0xf bank_mask:0xf
	v_add_f32_dpp v111, v111, v111 row_shr:8 row_mask:0xf bank_mask:0xf
	v_add_f32_dpp v104, v104, v104 row_bcast:15 row_mask:0xa bank_mask:0xf
	v_add_f32_dpp v105, v105, v105 row_bcast:15 row_mask:0xa bank_mask:0xf
	v_add_f32_dpp v106, v106, v106 row_bcast:15 row_mask:0xa bank_mask:0xf
	v_add_f32_dpp v107, v107, v107 row_bcast:15 row_mask:0xa bank_mask:0xf
	v_add_f32_dpp v108, v108, v108 row_bcast:15 row_mask:0xa bank_mask:0xf
	v_add_f32_dpp v109, v109, v109 row_bcast:15 row_mask:0xa bank_mask:0xf
	v_add_f32_dpp v110, v110, v110 row_bcast:15 row_mask:0xa bank_mask:0xf
	v_add_f32_dpp v111, v111, v111 row_bcast:15 row_mask:0xa bank_mask:0xf
	v_add_f32_dpp v104, v104, v104 row_bcast:31 row_mask:0xc bank_mask:0xf
	v_add_f32_dpp v105, v105, v105 row_bcast:31 row_mask:0xc bank_mask:0xf
	v_add_f32_dpp v106, v106, v106 row_bcast:31 row_mask:0xc bank_mask:0xf
	v_add_f32_dpp v107, v107, v107 row_bcast:31 row_mask:0xc bank_mask:0xf
	v_add_f32_dpp v108, v108, v108 row_bcast:31 row_mask:0xc bank_mask:0xf
	v_add_f32_dpp v109, v109, v109 row_bcast:31 row_mask:0xc bank_mask:0xf
	v_add_f32_dpp v110, v110, v110 row_bcast:31 row_mask:0xc bank_mask:0xf
	v_add_f32_dpp v111, v111, v111 row_bcast:31 row_mask:0xc bank_mask:0xf
	s_waitcnt vmcnt(8)
	v_add_f32_dpp v112, v112, v112 row_shr:1 row_mask:0xf bank_mask:0xf
	v_add_f32_dpp v113, v113, v113 row_shr:1 row_mask:0xf bank_mask:0xf
	v_add_f32_dpp v114, v114, v114 row_shr:1 row_mask:0xf bank_mask:0xf
	v_add_f32_dpp v115, v115, v115 row_shr:1 row_mask:0xf bank_mask:0xf
	v_add_f32_dpp v116, v116, v116 row_shr:1 row_mask:0xf bank_mask:0xf
	v_add_f32_dpp v117, v117, v117 row_shr:1 row_mask:0xf bank_mask:0xf
	v_add_f32_dpp v118, v118, v118 row_shr:1 row_mask:0xf bank_mask:0xf
	v_add_f32_dpp v119, v119, v119 row_shr:1 row_mask:0xf bank_mask:0xf
	v_add_f32_dpp v112, v112, v112 row_shr:2 row_mask:0xf bank_mask:0xf
	v_add_f32_dpp v113, v113, v113 row_shr:2 row_mask:0xf bank_mask:0xf
	v_add_f32_dpp v114, v114, v114 row_shr:2 row_mask:0xf bank_mask:0xf
	v_add_f32_dpp v115, v115, v115 row_shr:2 row_mask:0xf bank_mask:0xf
	v_add_f32_dpp v116, v116, v116 row_shr:2 row_mask:0xf bank_mask:0xf
	v_add_f32_dpp v117, v117, v117 row_shr:2 row_mask:0xf bank_mask:0xf
	v_add_f32_dpp v118, v118, v118 row_shr:2 row_mask:0xf bank_mask:0xf
	v_add_f32_dpp v119, v119, v119 row_shr:2 row_mask:0xf bank_mask:0xf
	v_add_f32_dpp v112, v112, v112 row_shr:4 row_mask:0xf bank_mask:0xf
	v_add_f32_dpp v113, v113, v113 row_shr:4 row_mask:0xf bank_mask:0xf
	v_add_f32_dpp v114, v114, v114 row_shr:4 row_mask:0xf bank_mask:0xf
	v_add_f32_dpp v115, v115, v115 row_shr:4 row_mask:0xf bank_mask:0xf
	v_add_f32_dpp v116, v116, v116 row_shr:4 row_mask:0xf bank_mask:0xf
	v_add_f32_dpp v117, v117, v117 row_shr:4 row_mask:0xf bank_mask:0xf
	v_add_f32_dpp v118, v118, v118 row_shr:4 row_mask:0xf bank_mask:0xf
	v_add_f32_dpp v119, v119, v119 row_shr:4 row_mask:0xf bank_mask:0xf
	v_add_f32_dpp v112, v112, v112 row_shr:8 row_mask:0xf bank_mask:0xf
	v_add_f32_dpp v113, v113, v113 row_shr:8 row_mask:0xf bank_mask:0xf
	v_add_f32_dpp v114, v114, v114 row_shr:8 row_mask:0xf bank_mask:0xf
	v_add_f32_dpp v115, v115, v115 row_shr:8 row_mask:0xf bank_mask:0xf
	v_add_f32_dpp v116, v116, v116 row_shr:8 row_mask:0xf bank_mask:0xf
	v_add_f32_dpp v117, v117, v117 row_shr:8 row_mask:0xf bank_mask:0xf
	v_add_f32_dpp v118, v118, v118 row_shr:8 row_mask:0xf bank_mask:0xf
	v_add_f32_dpp v119, v119, v119 row_shr:8 row_mask:0xf bank_mask:0xf
	v_add_f32_dpp v112, v112, v112 row_bcast:15 row_mask:0xa bank_mask:0xf
	v_add_f32_dpp v113, v113, v113 row_bcast:15 row_mask:0xa bank_mask:0xf
	v_add_f32_dpp v114, v114, v114 row_bcast:15 row_mask:0xa bank_mask:0xf
	v_add_f32_dpp v115, v115, v115 row_bcast:15 row_mask:0xa bank_mask:0xf
	v_add_f32_dpp v116, v116, v116 row_bcast:15 row_mask:0xa bank_mask:0xf
	v_add_f32_dpp v117, v117, v117 row_bcast:15 row_mask:0xa bank_mask:0xf
	v_add_f32_dpp v118, v118, v118 row_bcast:15 row_mask:0xa bank_mask:0xf
	v_add_f32_dpp v119, v119, v119 row_bcast:15 row_mask:0xa bank_mask:0xf
	v_add_f32_dpp v112, v112, v112 row_bcast:31 row_mask:0xc bank_mask:0xf
	v_add_f32_dpp v113, v113, v113 row_bcast:31 row_mask:0xc bank_mask:0xf
	v_add_f32_dpp v114, v114, v114 row_bcast:31 row_mask:0xc bank_mask:0xf
	v_add_f32_dpp v115, v115, v115 row_bcast:31 row_mask:0xc bank_mask:0xf
	v_add_f32_dpp v116, v116, v116 row_bcast:31 row_mask:0xc bank_mask:0xf
	v_add_f32_dpp v117, v117, v117 row_bcast:31 row_mask:0xc bank_mask:0xf
	v_add_f32_dpp v118, v118, v118 row_bcast:31 row_mask:0xc bank_mask:0xf
	v_add_f32_dpp v119, v119, v119 row_bcast:31 row_mask:0xc bank_mask:0xf
	s_waitcnt vmcnt(0)
	v_add_f32_dpp v120, v120, v120 row_shr:1 row_mask:0xf bank_mask:0xf
	v_add_f32_dpp v121, v121, v121 row_shr:1 row_mask:0xf bank_mask:0xf
	v_add_f32_dpp v122, v122, v122 row_shr:1 row_mask:0xf bank_mask:0xf
	v_add_f32_dpp v123, v123, v123 row_shr:1 row_mask:0xf bank_mask:0xf
	v_add_f32_dpp v124, v124, v124 row_shr:1 row_mask:0xf bank_mask:0xf
	v_add_f32_dpp v125, v125, v125 row_shr:1 row_mask:0xf bank_mask:0xf
	v_add_f32_dpp v126, v126, v126 row_shr:1 row_mask:0xf bank_mask:0xf
	v_add_f32_dpp v127, v127, v127 row_shr:1 row_mask:0xf bank_mask:0xf
	v_add_f32_dpp v120, v120, v120 row_shr:2 row_mask:0xf bank_mask:0xf
	v_add_f32_dpp v121, v121, v121 row_shr:2 row_mask:0xf bank_mask:0xf
	v_add_f32_dpp v122, v122, v122 row_shr:2 row_mask:0xf bank_mask:0xf
	v_add_f32_dpp v123, v123, v123 row_shr:2 row_mask:0xf bank_mask:0xf
	v_add_f32_dpp v124, v124, v124 row_shr:2 row_mask:0xf bank_mask:0xf
	v_add_f32_dpp v125, v125, v125 row_shr:2 row_mask:0xf bank_mask:0xf
	v_add_f32_dpp v126, v126, v126 row_shr:2 row_mask:0xf bank_mask:0xf
	v_add_f32_dpp v127, v127, v127 row_shr:2 row_mask:0xf bank_mask:0xf
	v_add_f32_dpp v120, v120, v120 row_shr:4 row_mask:0xf bank_mask:0xf
	v_add_f32_dpp v121, v121, v121 row_shr:4 row_mask:0xf bank_mask:0xf
	v_add_f32_dpp v122, v122, v122 row_shr:4 row_mask:0xf bank_mask:0xf
	v_add_f32_dpp v123, v123, v123 row_shr:4 row_mask:0xf bank_mask:0xf
	v_add_f32_dpp v124, v124, v124 row_shr:4 row_mask:0xf bank_mask:0xf
	v_add_f32_dpp v125, v125, v125 row_shr:4 row_mask:0xf bank_mask:0xf
	v_add_f32_dpp v126, v126, v126 row_shr:4 row_mask:0xf bank_mask:0xf
	v_add_f32_dpp v127, v127, v127 row_shr:4 row_mask:0xf bank_mask:0xf
	v_add_f32_dpp v120, v120, v120 row_shr:8 row_mask:0xf bank_mask:0xf
	v_add_f32_dpp v121, v121, v121 row_shr:8 row_mask:0xf bank_mask:0xf
	v_add_f32_dpp v122, v122, v122 row_shr:8 row_mask:0xf bank_mask:0xf
	v_add_f32_dpp v123, v123, v123 row_shr:8 row_mask:0xf bank_mask:0xf
	v_add_f32_dpp v124, v124, v124 row_shr:8 row_mask:0xf bank_mask:0xf
	v_add_f32_dpp v125, v125, v125 row_shr:8 row_mask:0xf bank_mask:0xf
	v_add_f32_dpp v126, v126, v126 row_shr:8 row_mask:0xf bank_mask:0xf
	v_add_f32_dpp v127, v127, v127 row_shr:8 row_mask:0xf bank_mask:0xf
	v_add_f32_dpp v120, v120, v120 row_bcast:15 row_mask:0xa bank_mask:0xf
	v_add_f32_dpp v121, v121, v121 row_bcast:15 row_mask:0xa bank_mask:0xf
	v_add_f32_dpp v122, v122, v122 row_bcast:15 row_mask:0xa bank_mask:0xf
	v_add_f32_dpp v123, v123, v123 row_bcast:15 row_mask:0xa bank_mask:0xf
	v_add_f32_dpp v124, v124, v124 row_bcast:15 row_mask:0xa bank_mask:0xf
	v_add_f32_dpp v125, v125, v125 row_bcast:15 row_mask:0xa bank_mask:0xf
	v_add_f32_dpp v126, v126, v126 row_bcast:15 row_mask:0xa bank_mask:0xf
	v_add_f32_dpp v127, v127, v127 row_bcast:15 row_mask:0xa bank_mask:0xf
	v_add_f32_dpp v120, v120, v120 row_bcast:31 row_mask:0xc bank_mask:0xf
	v_add_f32_dpp v121, v121, v121 row_bcast:31 row_mask:0xc bank_mask:0xf
	v_add_f32_dpp v122, v122, v122 row_bcast:31 row_mask:0xc bank_mask:0xf
	v_add_f32_dpp v123, v123, v123 row_bcast:31 row_mask:0xc bank_mask:0xf
	v_add_f32_dpp v124, v124, v124 row_bcast:31 row_mask:0xc bank_mask:0xf
	v_add_f32_dpp v125, v125, v125 row_bcast:31 row_mask:0xc bank_mask:0xf
	v_add_f32_dpp v126, v126, v126 row_bcast:31 row_mask:0xc bank_mask:0xf
	v_add_f32_dpp v127, v127, v127 row_bcast:31 row_mask:0xc bank_mask:0xf
	s_mov_b32 exec_lo, 0
	s_brev_b32 exec_hi, 1
	ds_write_b32 v11, v64
	ds_write_b32 v11, v65 offset:4
	ds_write_b32 v11, v66 offset:8
	ds_write_b32 v11, v67 offset:12
	ds_write_b32 v11, v68 offset:16
	ds_write_b32 v11, v69 offset:20
	ds_write_b32 v11, v70 offset:24
	ds_write_b32 v11, v71 offset:28
	ds_write_b32 v11, v72 offset:32
	ds_write_b32 v11, v73 offset:36
	ds_write_b32 v11, v74 offset:40
	ds_write_b32 v11, v75 offset:44
	ds_write_b32 v11, v76 offset:48
	ds_write_b32 v11, v77 offset:52
	ds_write_b32 v11, v78 offset:56
	ds_write_b32 v11, v79 offset:60
	ds_write_b32 v11, v80 offset:64
	ds_write_b32 v11, v81 offset:68
	ds_write_b32 v11, v82 offset:72
	ds_write_b32 v11, v83 offset:76
	ds_write_b32 v11, v84 offset:80
	ds_write_b32 v11, v85 offset:84
	ds_write_b32 v11, v86 offset:88
	ds_write_b32 v11, v87 offset:92
	ds_write_b32 v11, v88 offset:96
	ds_write_b32 v11, v89 offset:100
	ds_write_b32 v11, v90 offset:104
	ds_write_b32 v11, v91 offset:108
	ds_write_b32 v11, v92 offset:112
	ds_write_b32 v11, v93 offset:116
	ds_write_b32 v11, v94 offset:120
	ds_write_b32 v11, v95 offset:124
	ds_write_b32 v11, v96 offset:128
	ds_write_b32 v11, v97 offset:132
	ds_write_b32 v11, v98 offset:136
	ds_write_b32 v11, v99 offset:140
	ds_write_b32 v11, v100 offset:144
	ds_write_b32 v11, v101 offset:148
	ds_write_b32 v11, v102 offset:152
	ds_write_b32 v11, v103 offset:156
	ds_write_b32 v11, v104 offset:160
	ds_write_b32 v11, v105 offset:164
	ds_write_b32 v11, v106 offset:168
	ds_write_b32 v11, v107 offset:172
	ds_write_b32 v11, v108 offset:176
	ds_write_b32 v11, v109 offset:180
	ds_write_b32 v11, v110 offset:184
	ds_write_b32 v11, v111 offset:188
	ds_write_b32 v11, v112 offset:192
	ds_write_b32 v11, v113 offset:196
	ds_write_b32 v11, v114 offset:200
	ds_write_b32 v11, v115 offset:204
	ds_write_b32 v11, v116 offset:208
	ds_write_b32 v11, v117 offset:212
	ds_write_b32 v11, v118 offset:216
	ds_write_b32 v11, v119 offset:220
	ds_write_b32 v11, v120 offset:224
	ds_write_b32 v11, v121 offset:228
	ds_write_b32 v11, v122 offset:232
	ds_write_b32 v11, v123 offset:236
	ds_write_b32 v11, v124 offset:240
	ds_write_b32 v11, v125 offset:244
	ds_write_b32 v11, v126 offset:248
	ds_write_b32 v11, v127 offset:252
	s_mov_b64 exec, -1
	s_waitcnt lgkmcnt(0)
	ds_read_b32 v128, v10
	s_waitcnt lgkmcnt(0)
	s_nop 1
	v_add_f32_dpp v128, v128, v128 row_shr:1 row_mask:0xf bank_mask:0xf
	s_nop 1
	v_add_f32_dpp v128, v128, v128 row_shr:2 row_mask:0xf bank_mask:0xf
	s_nop 1
	v_add_f32_dpp v128, v128, v128 row_shr:4 row_mask:0xf bank_mask:0xf
	s_nop 1
	v_add_f32_dpp v128, v128, v128 row_shr:8 row_mask:0xf bank_mask:0xf
	s_nop 1
	v_add_f32_dpp v128, v128, v128 row_bcast:15 row_mask:0xa bank_mask:0xf
	s_nop 1
	v_add_f32_dpp v128, v128, v128 row_bcast:31 row_mask:0xc bank_mask:0xf
	s_nop 1
	v_readlane_b32 s47, v128, 0
	v_readlane_b32 s46, v128, 1
	s_nop 1
	v_mul_f32_e32 v64, 0x3fb8aa3b, v64
	global_store_dword v[12:13], v64, off
	v_add_f32_e32 v65, s47, v65
	v_readlane_b32 s47, v128, 2
	v_mul_f32_e32 v65, 0x3fb8aa3b, v65
	global_store_dword v[12:13], v65, off offset:256
	v_add_f32_e32 v66, s46, v66
	v_readlane_b32 s46, v128, 3
	v_mul_f32_e32 v66, 0x3fb8aa3b, v66
	global_store_dword v[12:13], v66, off offset:512
	v_add_f32_e32 v67, s47, v67
	v_readlane_b32 s47, v128, 4
	v_mul_f32_e32 v67, 0x3fb8aa3b, v67
	global_store_dword v[12:13], v67, off offset:768
	v_add_f32_e32 v68, s46, v68
	v_readlane_b32 s46, v128, 5
	v_mul_f32_e32 v68, 0x3fb8aa3b, v68
	global_store_dword v[12:13], v68, off offset:1024
	v_add_f32_e32 v69, s47, v69
	v_readlane_b32 s47, v128, 6
	v_mul_f32_e32 v69, 0x3fb8aa3b, v69
	global_store_dword v[12:13], v69, off offset:1280
	v_add_f32_e32 v70, s46, v70
	v_readlane_b32 s46, v128, 7
	v_mul_f32_e32 v70, 0x3fb8aa3b, v70
	global_store_dword v[12:13], v70, off offset:1536
	v_add_f32_e32 v71, s47, v71
	v_readlane_b32 s47, v128, 8
	v_mul_f32_e32 v71, 0x3fb8aa3b, v71
	global_store_dword v[12:13], v71, off offset:1792
	v_add_f32_e32 v72, s46, v72
	v_readlane_b32 s46, v128, 9
	v_mul_f32_e32 v72, 0x3fb8aa3b, v72
	global_store_dword v[12:13], v72, off offset:2048
	v_add_f32_e32 v73, s47, v73
	v_readlane_b32 s47, v128, 10
	v_mul_f32_e32 v73, 0x3fb8aa3b, v73
	global_store_dword v[12:13], v73, off offset:2304
	v_add_f32_e32 v74, s46, v74
	v_readlane_b32 s46, v128, 11
	v_mul_f32_e32 v74, 0x3fb8aa3b, v74
	global_store_dword v[12:13], v74, off offset:2560
	v_add_f32_e32 v75, s47, v75
	v_readlane_b32 s47, v128, 12
	v_mul_f32_e32 v75, 0x3fb8aa3b, v75
	global_store_dword v[12:13], v75, off offset:2816
	v_add_f32_e32 v76, s46, v76
	v_readlane_b32 s46, v128, 13
	v_mul_f32_e32 v76, 0x3fb8aa3b, v76
	global_store_dword v[12:13], v76, off offset:3072
	v_add_f32_e32 v77, s47, v77
	v_readlane_b32 s47, v128, 14
	v_mul_f32_e32 v77, 0x3fb8aa3b, v77
	global_store_dword v[12:13], v77, off offset:3328
	v_add_f32_e32 v78, s46, v78
	v_readlane_b32 s46, v128, 15
	v_mul_f32_e32 v78, 0x3fb8aa3b, v78
	global_store_dword v[12:13], v78, off offset:3584
	v_add_f32_e32 v79, s47, v79
	v_readlane_b32 s47, v128, 16
	v_mul_f32_e32 v79, 0x3fb8aa3b, v79
	global_store_dword v[12:13], v79, off offset:3840
	v_lshl_add_u64 v[12:13], v[12:13], 0, s[42:43]
	v_add_f32_e32 v80, s46, v80
	v_readlane_b32 s46, v128, 17
	v_mul_f32_e32 v80, 0x3fb8aa3b, v80
	global_store_dword v[12:13], v80, off
	v_add_f32_e32 v81, s47, v81
	v_readlane_b32 s47, v128, 18
	v_mul_f32_e32 v81, 0x3fb8aa3b, v81
	global_store_dword v[12:13], v81, off offset:256
	v_add_f32_e32 v82, s46, v82
	v_readlane_b32 s46, v128, 19
	v_mul_f32_e32 v82, 0x3fb8aa3b, v82
	global_store_dword v[12:13], v82, off offset:512
	v_add_f32_e32 v83, s47, v83
	v_readlane_b32 s47, v128, 20
	v_mul_f32_e32 v83, 0x3fb8aa3b, v83
	global_store_dword v[12:13], v83, off offset:768
	v_add_f32_e32 v84, s46, v84
	v_readlane_b32 s46, v128, 21
	v_mul_f32_e32 v84, 0x3fb8aa3b, v84
	global_store_dword v[12:13], v84, off offset:1024
	v_add_f32_e32 v85, s47, v85
	v_readlane_b32 s47, v128, 22
	v_mul_f32_e32 v85, 0x3fb8aa3b, v85
	global_store_dword v[12:13], v85, off offset:1280
	v_add_f32_e32 v86, s46, v86
	v_readlane_b32 s46, v128, 23
	v_mul_f32_e32 v86, 0x3fb8aa3b, v86
	global_store_dword v[12:13], v86, off offset:1536
	v_add_f32_e32 v87, s47, v87
	v_readlane_b32 s47, v128, 24
	v_mul_f32_e32 v87, 0x3fb8aa3b, v87
	global_store_dword v[12:13], v87, off offset:1792
	v_add_f32_e32 v88, s46, v88
	v_readlane_b32 s46, v128, 25
	v_mul_f32_e32 v88, 0x3fb8aa3b, v88
	global_store_dword v[12:13], v88, off offset:2048
	v_add_f32_e32 v89, s47, v89
	v_readlane_b32 s47, v128, 26
	v_mul_f32_e32 v89, 0x3fb8aa3b, v89
	global_store_dword v[12:13], v89, off offset:2304
	v_add_f32_e32 v90, s46, v90
	v_readlane_b32 s46, v128, 27
	v_mul_f32_e32 v90, 0x3fb8aa3b, v90
	global_store_dword v[12:13], v90, off offset:2560
	v_add_f32_e32 v91, s47, v91
	v_readlane_b32 s47, v128, 28
	v_mul_f32_e32 v91, 0x3fb8aa3b, v91
	global_store_dword v[12:13], v91, off offset:2816
	v_add_f32_e32 v92, s46, v92
	v_readlane_b32 s46, v128, 29
	v_mul_f32_e32 v92, 0x3fb8aa3b, v92
	global_store_dword v[12:13], v92, off offset:3072
	v_add_f32_e32 v93, s47, v93
	v_readlane_b32 s47, v128, 30
	v_mul_f32_e32 v93, 0x3fb8aa3b, v93
	global_store_dword v[12:13], v93, off offset:3328
	v_add_f32_e32 v94, s46, v94
	v_readlane_b32 s46, v128, 31
	v_mul_f32_e32 v94, 0x3fb8aa3b, v94
	global_store_dword v[12:13], v94, off offset:3584
	v_add_f32_e32 v95, s47, v95
	v_readlane_b32 s47, v128, 32
	v_mul_f32_e32 v95, 0x3fb8aa3b, v95
	global_store_dword v[12:13], v95, off offset:3840
	v_lshl_add_u64 v[12:13], v[12:13], 0, s[42:43]
	v_add_f32_e32 v96, s46, v96
	v_readlane_b32 s46, v128, 33
	v_mul_f32_e32 v96, 0x3fb8aa3b, v96
	global_store_dword v[12:13], v96, off
	v_add_f32_e32 v97, s47, v97
	v_readlane_b32 s47, v128, 34
	v_mul_f32_e32 v97, 0x3fb8aa3b, v97
	global_store_dword v[12:13], v97, off offset:256
	v_add_f32_e32 v98, s46, v98
	v_readlane_b32 s46, v128, 35
	v_mul_f32_e32 v98, 0x3fb8aa3b, v98
	global_store_dword v[12:13], v98, off offset:512
	v_add_f32_e32 v99, s47, v99
	v_readlane_b32 s47, v128, 36
	v_mul_f32_e32 v99, 0x3fb8aa3b, v99
	global_store_dword v[12:13], v99, off offset:768
	v_add_f32_e32 v100, s46, v100
	v_readlane_b32 s46, v128, 37
	v_mul_f32_e32 v100, 0x3fb8aa3b, v100
	global_store_dword v[12:13], v100, off offset:1024
	v_add_f32_e32 v101, s47, v101
	v_readlane_b32 s47, v128, 38
	v_mul_f32_e32 v101, 0x3fb8aa3b, v101
	global_store_dword v[12:13], v101, off offset:1280
	v_add_f32_e32 v102, s46, v102
	v_readlane_b32 s46, v128, 39
	v_mul_f32_e32 v102, 0x3fb8aa3b, v102
	global_store_dword v[12:13], v102, off offset:1536
	v_add_f32_e32 v103, s47, v103
	v_readlane_b32 s47, v128, 40
	v_mul_f32_e32 v103, 0x3fb8aa3b, v103
	global_store_dword v[12:13], v103, off offset:1792
	v_add_f32_e32 v104, s46, v104
	v_readlane_b32 s46, v128, 41
	v_mul_f32_e32 v104, 0x3fb8aa3b, v104
	global_store_dword v[12:13], v104, off offset:2048
	v_add_f32_e32 v105, s47, v105
	v_readlane_b32 s47, v128, 42
	v_mul_f32_e32 v105, 0x3fb8aa3b, v105
	global_store_dword v[12:13], v105, off offset:2304
	v_add_f32_e32 v106, s46, v106
	v_readlane_b32 s46, v128, 43
	v_mul_f32_e32 v106, 0x3fb8aa3b, v106
	global_store_dword v[12:13], v106, off offset:2560
	v_add_f32_e32 v107, s47, v107
	v_readlane_b32 s47, v128, 44
	v_mul_f32_e32 v107, 0x3fb8aa3b, v107
	global_store_dword v[12:13], v107, off offset:2816
	v_add_f32_e32 v108, s46, v108
	v_readlane_b32 s46, v128, 45
	v_mul_f32_e32 v108, 0x3fb8aa3b, v108
	global_store_dword v[12:13], v108, off offset:3072
	v_add_f32_e32 v109, s47, v109
	v_readlane_b32 s47, v128, 46
	v_mul_f32_e32 v109, 0x3fb8aa3b, v109
	global_store_dword v[12:13], v109, off offset:3328
	v_add_f32_e32 v110, s46, v110
	v_readlane_b32 s46, v128, 47
	v_mul_f32_e32 v110, 0x3fb8aa3b, v110
	global_store_dword v[12:13], v110, off offset:3584
	v_add_f32_e32 v111, s47, v111
	v_readlane_b32 s47, v128, 48
	v_mul_f32_e32 v111, 0x3fb8aa3b, v111
	global_store_dword v[12:13], v111, off offset:3840
	v_lshl_add_u64 v[12:13], v[12:13], 0, s[42:43]
	v_add_f32_e32 v112, s46, v112
	v_readlane_b32 s46, v128, 49
	v_mul_f32_e32 v112, 0x3fb8aa3b, v112
	global_store_dword v[12:13], v112, off
	v_add_f32_e32 v113, s47, v113
	v_readlane_b32 s47, v128, 50
	v_mul_f32_e32 v113, 0x3fb8aa3b, v113
	global_store_dword v[12:13], v113, off offset:256
	v_add_f32_e32 v114, s46, v114
	v_readlane_b32 s46, v128, 51
	v_mul_f32_e32 v114, 0x3fb8aa3b, v114
	global_store_dword v[12:13], v114, off offset:512
	v_add_f32_e32 v115, s47, v115
	v_readlane_b32 s47, v128, 52
	v_mul_f32_e32 v115, 0x3fb8aa3b, v115
	global_store_dword v[12:13], v115, off offset:768
	v_add_f32_e32 v116, s46, v116
	v_readlane_b32 s46, v128, 53
	v_mul_f32_e32 v116, 0x3fb8aa3b, v116
	global_store_dword v[12:13], v116, off offset:1024
	v_add_f32_e32 v117, s47, v117
	v_readlane_b32 s47, v128, 54
	v_mul_f32_e32 v117, 0x3fb8aa3b, v117
	global_store_dword v[12:13], v117, off offset:1280
	v_add_f32_e32 v118, s46, v118
	v_readlane_b32 s46, v128, 55
	v_mul_f32_e32 v118, 0x3fb8aa3b, v118
	global_store_dword v[12:13], v118, off offset:1536
	v_add_f32_e32 v119, s47, v119
	v_readlane_b32 s47, v128, 56
	v_mul_f32_e32 v119, 0x3fb8aa3b, v119
	global_store_dword v[12:13], v119, off offset:1792
	v_add_f32_e32 v120, s46, v120
	v_readlane_b32 s46, v128, 57
	v_mul_f32_e32 v120, 0x3fb8aa3b, v120
	global_store_dword v[12:13], v120, off offset:2048
	v_add_f32_e32 v121, s47, v121
	v_readlane_b32 s47, v128, 58
	v_mul_f32_e32 v121, 0x3fb8aa3b, v121
	global_store_dword v[12:13], v121, off offset:2304
	v_add_f32_e32 v122, s46, v122
	v_readlane_b32 s46, v128, 59
	v_mul_f32_e32 v122, 0x3fb8aa3b, v122
	global_store_dword v[12:13], v122, off offset:2560
	v_add_f32_e32 v123, s47, v123
	v_readlane_b32 s47, v128, 60
	v_mul_f32_e32 v123, 0x3fb8aa3b, v123
	global_store_dword v[12:13], v123, off offset:2816
	v_add_f32_e32 v124, s46, v124
	v_readlane_b32 s46, v128, 61
	v_mul_f32_e32 v124, 0x3fb8aa3b, v124
	global_store_dword v[12:13], v124, off offset:3072
	v_add_f32_e32 v125, s47, v125
	v_readlane_b32 s47, v128, 62
	v_mul_f32_e32 v125, 0x3fb8aa3b, v125
	global_store_dword v[12:13], v125, off offset:3328
	v_add_f32_e32 v126, s46, v126
	v_mul_f32_e32 v126, 0x3fb8aa3b, v126
	global_store_dword v[12:13], v126, off offset:3584
	v_add_f32_e32 v127, s47, v127
	v_mul_f32_e32 v127, 0x3fb8aa3b, v127
	global_store_dword v[12:13], v127, off offset:3840
	s_add_i32 s69, s69, s72
	s_cmpk_lt_i32 s69, 0x100
	s_cbranch_scc1 .LBB0_69
